# PROJ forget-gate epilogue: logf expansion simplified (denormal pre-scale and inf check are never taken for an argument in (lb,1); ln2 product as one f32 multiply; result is stored as fp16 as before)
# speedup vs baseline: 1.0164x; 1.0164x over previous
; __device__ __forceinline__ float sigmoidf_(float z) { return __builtin_amdgcn_rcpf(1.0f + __builtin_amdgcn_exp2f(-1.4426950408889634f * z)); }
; __device__ __forceinline__ u32x4 pack8(const float (&f)[8]) { u32x4 w; w.x = pk2(f[0], f[1]); w.y = pk2(f[2], f[3]); w.z = pk2(f[4], f[5]); w.w = pk2(f[6], f[7]); return w; }
;     __device__ __forceinline__ float compute(const Pre& p, f32x4 (&acc)[2][2][4][2], const f32x4 (&cv)[2][2], const pg8::Unit& u, int ai, int m, int wr, int wc, int fr, int fq) const {
;     ...
;             if (MODE == EM_PROJ) {
;                 const int pn = u.pn;
;                 if (pn < 16) {
;                     const int sec = pn >> 2, col = (pn & 3) * 256 + ct; const size_t o = (size_t)row * 1024 + col;
;                     if (sec == 0) { float w[8];
; #pragma unroll
;                         for (int j = 0; j < 8; ++j) w[j] = v[j] * rs;
;                         __builtin_nontemporal_store(pack8(w), (u32x4*)((bf16_t*)(ws + WS_Q) + o));
;                     } else if (sec == 1) {
;                         float lf[8];
; #pragma unroll
;                         for (int j = 0; j < 8; ++j) { const float lb = j < 4 ? cv[bj][0][j] : cv[bj][1][j - 4]; const float sg = sigmoidf_(v[j] * rs); lf[j] = __logf(lb + (1.f - lb) * sg); }
;                         u32x4 hw; hw.x = pkh2(lf[0], lf[1]); hw.y = pkh2(lf[2], lf[3]); hw.z = pkh2(lf[4], lf[5]); hw.w = pkh2(lf[6], lf[7]);
;                         __builtin_nontemporal_store(hw, (u32x4*)((_Float16*)out + o));
.LBB0_269:
	v_mul_f32_e32 v187, v141, v182
	v_mul_f32_e32 v187, 0xbfb8aa3b, v187
	v_add_f32_e32 v140, 1.0, v140
	v_exp_f32_e32 v187, v187
	v_rcp_f32_e32 v140, v140
	v_add_f32_e32 v187, 1.0, v187
	v_fma_f32 v140, v201, v140, v36
	v_rcp_f32_e32 v187, v187
	s_nop 0
	v_fma_f32 v187, v199, v187, v37
	v_log_f32_e32 v140, v140
	s_nop 0
	v_mul_f32_e32 v200, 0x3f317217, v140
	v_mul_f32_e32 v202, v142, v182
	v_mul_f32_e32 v202, 0xbfb8aa3b, v202
	v_log_f32_e32 v187, v187
	v_exp_f32_e32 v202, v202
	s_nop 0
	v_add_f32_e32 v202, 1.0, v202
	v_rcp_f32_e32 v202, v202
	v_mov_b32_e32 v140, v200
	v_mul_f32_e32 v200, 0x3f317217, v187
	v_mov_b32_e32 v187, v200
	v_fma_f32 v200, v198, v202, v38
	v_mul_f32_e32 v202, v143, v182
	v_mul_f32_e32 v202, 0xbfb8aa3b, v202
	v_exp_f32_e32 v202, v202
	v_log_f32_e32 v200, v200
	v_add_f32_e32 v202, 1.0, v202
	v_rcp_f32_e32 v202, v202
	v_mul_f32_e32 v204, 0x3f317217, v200
	v_fma_f32 v202, v197, v202, v39
	v_mov_b32_e32 v200, v204
	v_mul_f32_e32 v204, v136, v182
	v_mul_f32_e32 v204, 0xbfb8aa3b, v204
	v_exp_f32_e32 v204, v204
	v_log_f32_e32 v202, v202
	v_add_f32_e32 v204, 1.0, v204
	v_rcp_f32_e32 v204, v204
	v_mul_f32_e32 v205, 0x3f317217, v202
	v_fma_f32 v204, v196, v204, v32
	v_mul_f32_e32 v206, v137, v182
	v_mul_f32_e32 v206, 0xbfb8aa3b, v206
	v_log_f32_e32 v204, v204
	v_exp_f32_e32 v206, v206
	v_mov_b32_e32 v202, v205
	v_mul_f32_e32 v205, 0x3f317217, v204
	v_add_f32_e32 v206, 1.0, v206
	v_rcp_f32_e32 v206, v206
	v_mov_b32_e32 v204, v205
	v_mov_b32_e32 v207, v204
	v_fma_f32 v204, v195, v206, v33
	v_mul_f32_e32 v205, v138, v182
	v_mul_f32_e32 v205, 0xbfb8aa3b, v205
	v_exp_f32_e32 v205, v205
	v_log_f32_e32 v204, v204
	v_add_f32_e32 v205, 1.0, v205
	v_rcp_f32_e32 v205, v205
	v_mul_f32_e32 v206, 0x3f317217, v204
	v_fma_f32 v205, v194, v205, v34
	v_mov_b32_e32 v204, v206
	v_mov_b32_e32 v208, v204
	v_mul_f32_e32 v206, v139, v182
	v_mul_f32_e32 v206, 0xbfb8aa3b, v206
	v_exp_f32_e32 v206, v206
	v_log_f32_e32 v205, v205
	v_add_f32_e32 v206, 1.0, v206
	v_rcp_f32_e32 v206, v206
	v_mul_f32_e32 v204, 0x3f317217, v205
	v_fma_f32 v206, v193, v206, v35
	v_log_f32_e32 v206, v206
	v_mov_b32_e32 v209, v204
	v_mul_f32_e32 v204, 0x3f317217, v206
	v_mov_b32_e32 v210, v204
	v_cvt_pk_f16_f32 v204, v140, v187
	v_cvt_pk_f16_f32 v205, v200, v202
	v_cvt_pk_f16_f32 v206, v207, v208
	v_cvt_pk_f16_f32 v207, v209, v210
	v_lshl_add_u64 v[208:209], v[188:189], 1, s[70:71]
	global_store_dwordx4 v[208:209], v[204:207], off nt

; __device__ __forceinline__ float sigmoidf_(float z) { return __builtin_amdgcn_rcpf(1.0f + __builtin_amdgcn_exp2f(-1.4426950408889634f * z)); }
; __device__ __forceinline__ u32x4 pack8(const float (&f)[8]) { u32x4 w; w.x = pk2(f[0], f[1]); w.y = pk2(f[2], f[3]); w.z = pk2(f[4], f[5]); w.w = pk2(f[6], f[7]); return w; }
;     __device__ __forceinline__ float compute(const Pre& p, f32x4 (&acc)[2][2][4][2], const f32x4 (&cv)[2][2], const pg8::Unit& u, int ai, int m, int wr, int wc, int fr, int fq) const {
;     ...
;             if (MODE == EM_PROJ) {
;                 const int pn = u.pn;
;                 if (pn < 16) {
;                     const int sec = pn >> 2, col = (pn & 3) * 256 + ct; const size_t o = (size_t)row * 1024 + col;
;                     if (sec == 0) { float w[8];
; #pragma unroll
;                         for (int j = 0; j < 8; ++j) w[j] = v[j] * rs;
;                         __builtin_nontemporal_store(pack8(w), (u32x4*)((bf16_t*)(ws + WS_Q) + o));
;                     } else if (sec == 1) {
;                         float lf[8];
; #pragma unroll
;                         for (int j = 0; j < 8; ++j) { const float lb = j < 4 ? cv[bj][0][j] : cv[bj][1][j - 4]; const float sg = sigmoidf_(v[j] * rs); lf[j] = __logf(lb + (1.f - lb) * sg); }
;                         u32x4 hw; hw.x = pkh2(lf[0], lf[1]); hw.y = pkh2(lf[2], lf[3]); hw.z = pkh2(lf[4], lf[5]); hw.w = pkh2(lf[6], lf[7]);
;                         __builtin_nontemporal_store(hw, (u32x4*)((_Float16*)out + o));
.LBB0_285:
	v_mul_f32_e32 v139, v133, v182
	v_mul_f32_e32 v139, 0xbfb8aa3b, v139
	v_add_f32_e32 v132, 1.0, v132
	v_exp_f32_e32 v139, v139
	v_rcp_f32_e32 v132, v132
	v_lshl_add_u64 v[184:185], v[184:185], 0, v[168:169]
	v_lshl_add_u64 v[184:185], v[184:185], 1, s[70:71]
	v_add_f32_e32 v139, 1.0, v139
	v_fma_f32 v132, v202, v132, v20
	v_rcp_f32_e32 v139, v139
	s_nop 0
	v_fma_f32 v139, v200, v139, v21
	v_log_f32_e32 v132, v132
	s_nop 0
	v_mul_f32_e32 v206, 0x3f317217, v132
	v_mul_f32_e32 v207, v134, v182
	v_mul_f32_e32 v207, 0xbfb8aa3b, v207
	v_log_f32_e32 v139, v139
	v_exp_f32_e32 v207, v207
	s_nop 0
	v_add_f32_e32 v207, 1.0, v207
	v_rcp_f32_e32 v207, v207
	v_mov_b32_e32 v132, v206
	v_mul_f32_e32 v206, 0x3f317217, v139
	v_mov_b32_e32 v139, v206
	v_fma_f32 v206, v189, v207, v22
	v_mul_f32_e32 v207, v135, v182
	v_mul_f32_e32 v207, 0xbfb8aa3b, v207
	v_exp_f32_e32 v207, v207
	v_log_f32_e32 v206, v206
	v_add_f32_e32 v207, 1.0, v207
	v_rcp_f32_e32 v207, v207
	v_mul_f32_e32 v208, 0x3f317217, v206
	v_fma_f32 v207, v188, v207, v23
	v_mov_b32_e32 v206, v208
	v_mov_b32_e32 v209, v206
	v_mul_f32_e32 v208, v128, v182
	v_mul_f32_e32 v208, 0xbfb8aa3b, v208
	v_exp_f32_e32 v208, v208
	v_log_f32_e32 v207, v207
	v_add_f32_e32 v208, 1.0, v208
	v_rcp_f32_e32 v208, v208
	v_mul_f32_e32 v206, 0x3f317217, v207
	v_fma_f32 v208, v187, v208, v16
	v_mul_f32_e32 v210, v129, v182
	v_mul_f32_e32 v210, 0xbfb8aa3b, v210
	v_log_f32_e32 v208, v208
	v_exp_f32_e32 v210, v210
	v_mov_b32_e32 v207, v206
	v_mul_f32_e32 v206, 0x3f317217, v208
	v_add_f32_e32 v210, 1.0, v210
	v_rcp_f32_e32 v210, v210
	v_cvt_pk_f16_f32 v207, v209, v207
	v_mov_b32_e32 v208, v206
	v_fma_f32 v206, v186, v210, v17
	v_mul_f32_e32 v210, v130, v182
	v_mul_f32_e32 v210, 0xbfb8aa3b, v210
	v_exp_f32_e32 v210, v210
	v_log_f32_e32 v206, v206
	v_add_f32_e32 v210, 1.0, v210
	v_rcp_f32_e32 v210, v210
	v_mul_f32_e32 v211, 0x3f317217, v206
	v_fma_f32 v210, v143, v210, v18
	v_mov_b32_e32 v206, v211
	v_mov_b32_e32 v212, v206
	v_cvt_pk_f16_f32 v208, v208, v212
	v_mul_f32_e32 v211, v131, v182
	v_mul_f32_e32 v211, 0xbfb8aa3b, v211
	v_exp_f32_e32 v211, v211
	v_log_f32_e32 v210, v210
	v_add_f32_e32 v211, 1.0, v211
	v_rcp_f32_e32 v211, v211
	v_mul_f32_e32 v206, 0x3f317217, v210
	v_fma_f32 v211, v142, v211, v19
	v_log_f32_e32 v211, v211
	v_mov_b32_e32 v210, v206
	v_mul_f32_e32 v206, 0x3f317217, v211
	v_mov_b32_e32 v211, v206
	v_cvt_pk_f16_f32 v206, v132, v139
	v_cvt_pk_f16_f32 v209, v210, v211
	global_store_dwordx4 v[184:185], v[206:209], off offset:256 nt

; __device__ __forceinline__ float sigmoidf_(float z) { return __builtin_amdgcn_rcpf(1.0f + __builtin_amdgcn_exp2f(-1.4426950408889634f * z)); }
; __device__ __forceinline__ u32x4 pack8(const float (&f)[8]) { u32x4 w; w.x = pk2(f[0], f[1]); w.y = pk2(f[2], f[3]); w.z = pk2(f[4], f[5]); w.w = pk2(f[6], f[7]); return w; }
;     __device__ __forceinline__ float compute(const Pre& p, f32x4 (&acc)[2][2][4][2], const f32x4 (&cv)[2][2], const pg8::Unit& u, int ai, int m, int wr, int wc, int fr, int fq) const {
;     ...
;             if (MODE == EM_PROJ) {
;                 const int pn = u.pn;
;                 if (pn < 16) {
;                     const int sec = pn >> 2, col = (pn & 3) * 256 + ct; const size_t o = (size_t)row * 1024 + col;
;                     if (sec == 0) { float w[8];
; #pragma unroll
;                         for (int j = 0; j < 8; ++j) w[j] = v[j] * rs;
;                         __builtin_nontemporal_store(pack8(w), (u32x4*)((bf16_t*)(ws + WS_Q) + o));
;                     } else if (sec == 1) {
;                         float lf[8];
; #pragma unroll
;                         for (int j = 0; j < 8; ++j) { const float lb = j < 4 ? cv[bj][0][j] : cv[bj][1][j - 4]; const float sg = sigmoidf_(v[j] * rs); lf[j] = __logf(lb + (1.f - lb) * sg); }
;                         u32x4 hw; hw.x = pkh2(lf[0], lf[1]); hw.y = pkh2(lf[2], lf[3]); hw.z = pkh2(lf[4], lf[5]); hw.w = pkh2(lf[6], lf[7]);
;                         __builtin_nontemporal_store(hw, (u32x4*)((_Float16*)out + o));
.LBB0_301:
	v_mul_f32_e32 v131, v125, v180
	v_mul_f32_e32 v131, 0xbfb8aa3b, v131
	v_add_f32_e32 v124, 1.0, v124
	v_exp_f32_e32 v131, v131
	v_rcp_f32_e32 v124, v124
	v_add_f32_e32 v131, 1.0, v131
	v_fma_f32 v124, v201, v124, v36
	v_rcp_f32_e32 v131, v131
	s_nop 0
	v_fma_f32 v131, v199, v131, v37
	v_log_f32_e32 v124, v124
	s_nop 0
	v_mul_f32_e32 v134, 0x3f317217, v124
	v_mul_f32_e32 v135, v126, v180
	v_mul_f32_e32 v135, 0xbfb8aa3b, v135
	v_log_f32_e32 v131, v131
	v_exp_f32_e32 v135, v135
	s_nop 0
	v_add_f32_e32 v135, 1.0, v135
	v_rcp_f32_e32 v135, v135
	v_mov_b32_e32 v124, v134
	v_mul_f32_e32 v134, 0x3f317217, v131
	v_mov_b32_e32 v131, v134
	v_fma_f32 v134, v198, v135, v38
	v_mul_f32_e32 v135, v127, v180
	v_mul_f32_e32 v135, 0xbfb8aa3b, v135
	v_exp_f32_e32 v135, v135
	v_log_f32_e32 v134, v134
	v_add_f32_e32 v135, 1.0, v135
	v_rcp_f32_e32 v135, v135
	v_mul_f32_e32 v138, 0x3f317217, v134
	v_fma_f32 v135, v197, v135, v39
	v_mov_b32_e32 v134, v138
	v_mul_f32_e32 v138, v120, v180
	v_mul_f32_e32 v138, 0xbfb8aa3b, v138
	v_exp_f32_e32 v138, v138
	v_log_f32_e32 v135, v135
	v_add_f32_e32 v138, 1.0, v138
	v_rcp_f32_e32 v138, v138
	v_mul_f32_e32 v139, 0x3f317217, v135
	v_fma_f32 v138, v196, v138, v32
	v_mul_f32_e32 v140, v121, v180
	v_mul_f32_e32 v140, 0xbfb8aa3b, v140
	v_log_f32_e32 v138, v138
	v_exp_f32_e32 v140, v140
	v_mov_b32_e32 v135, v139
	v_mul_f32_e32 v139, 0x3f317217, v138
	v_add_f32_e32 v140, 1.0, v140
	v_rcp_f32_e32 v140, v140
	v_mov_b32_e32 v138, v139
	v_mov_b32_e32 v141, v138
	v_fma_f32 v138, v195, v140, v33
	v_mul_f32_e32 v139, v122, v180
	v_mul_f32_e32 v139, 0xbfb8aa3b, v139
	v_exp_f32_e32 v139, v139
	v_log_f32_e32 v138, v138
	v_add_f32_e32 v139, 1.0, v139
	v_rcp_f32_e32 v139, v139
	v_mul_f32_e32 v140, 0x3f317217, v138
	v_fma_f32 v139, v194, v139, v34
	v_mov_b32_e32 v138, v140
	v_mov_b32_e32 v182, v138
	v_mul_f32_e32 v140, v123, v180
	v_mul_f32_e32 v140, 0xbfb8aa3b, v140
	v_exp_f32_e32 v140, v140
	v_log_f32_e32 v139, v139
	v_add_f32_e32 v140, 1.0, v140
	v_rcp_f32_e32 v140, v140
	v_mul_f32_e32 v138, 0x3f317217, v139
	v_fma_f32 v140, v193, v140, v35
	v_log_f32_e32 v140, v140
	v_mov_b32_e32 v184, v138
	v_mul_f32_e32 v138, 0x3f317217, v140
	v_mov_b32_e32 v185, v138
	v_cvt_pk_f16_f32 v138, v124, v131
	v_cvt_pk_f16_f32 v139, v134, v135
	v_cvt_pk_f16_f32 v140, v141, v182
	v_cvt_pk_f16_f32 v141, v184, v185
	v_lshl_add_u64 v[134:135], v[132:133], 1, s[70:71]
	global_store_dwordx4 v[134:135], v[138:141], off nt

; __device__ __forceinline__ float sigmoidf_(float z) { return __builtin_amdgcn_rcpf(1.0f + __builtin_amdgcn_exp2f(-1.4426950408889634f * z)); }
; __device__ __forceinline__ u32x4 pack8(const float (&f)[8]) { u32x4 w; w.x = pk2(f[0], f[1]); w.y = pk2(f[2], f[3]); w.z = pk2(f[4], f[5]); w.w = pk2(f[6], f[7]); return w; }
;     __device__ __forceinline__ float compute(const Pre& p, f32x4 (&acc)[2][2][4][2], const f32x4 (&cv)[2][2], const pg8::Unit& u, int ai, int m, int wr, int wc, int fr, int fq) const {
;     ...
;             if (MODE == EM_PROJ) {
;                 const int pn = u.pn;
;                 if (pn < 16) {
;                     const int sec = pn >> 2, col = (pn & 3) * 256 + ct; const size_t o = (size_t)row * 1024 + col;
;                     if (sec == 0) { float w[8];
; #pragma unroll
;                         for (int j = 0; j < 8; ++j) w[j] = v[j] * rs;
;                         __builtin_nontemporal_store(pack8(w), (u32x4*)((bf16_t*)(ws + WS_Q) + o));
;                     } else if (sec == 1) {
;                         float lf[8];
; #pragma unroll
;                         for (int j = 0; j < 8; ++j) { const float lb = j < 4 ? cv[bj][0][j] : cv[bj][1][j - 4]; const float sg = sigmoidf_(v[j] * rs); lf[j] = __logf(lb + (1.f - lb) * sg); }
;                         u32x4 hw; hw.x = pkh2(lf[0], lf[1]); hw.y = pkh2(lf[2], lf[3]); hw.z = pkh2(lf[4], lf[5]); hw.w = pkh2(lf[6], lf[7]);
;                         __builtin_nontemporal_store(hw, (u32x4*)((_Float16*)out + o));
.LBB0_317:
	v_mul_f32_e32 v121, v117, v180
	v_mul_f32_e32 v121, 0xbfb8aa3b, v121
	v_add_f32_e32 v116, 1.0, v116
	v_exp_f32_e32 v121, v121
	v_rcp_f32_e32 v116, v116
	v_lshl_add_u64 v[128:129], v[128:129], 0, v[168:169]
	v_lshl_add_u64 v[128:129], v[128:129], 1, s[70:71]
	v_add_f32_e32 v121, 1.0, v121
	v_fma_f32 v116, v202, v116, v20
	v_rcp_f32_e32 v121, v121
	s_nop 0
	v_fma_f32 v121, v200, v121, v21
	v_log_f32_e32 v116, v116
	s_nop 0
	v_mul_f32_e32 v124, 0x3f317217, v116
	v_mul_f32_e32 v125, v118, v180
	v_mul_f32_e32 v125, 0xbfb8aa3b, v125
	v_log_f32_e32 v121, v121
	v_exp_f32_e32 v125, v125
	s_nop 0
	v_add_f32_e32 v125, 1.0, v125
	v_rcp_f32_e32 v125, v125
	v_mov_b32_e32 v116, v124
	v_mul_f32_e32 v124, 0x3f317217, v121
	v_mov_b32_e32 v121, v124
	v_fma_f32 v124, v189, v125, v22
	v_mul_f32_e32 v125, v119, v180
	v_mul_f32_e32 v125, 0xbfb8aa3b, v125
	v_exp_f32_e32 v125, v125
	v_log_f32_e32 v124, v124
	v_add_f32_e32 v125, 1.0, v125
	v_rcp_f32_e32 v125, v125
	v_mul_f32_e32 v126, 0x3f317217, v124
	v_fma_f32 v125, v188, v125, v23
	v_mov_b32_e32 v124, v126
	v_mov_b32_e32 v127, v124
	v_mul_f32_e32 v126, v112, v180
	v_mul_f32_e32 v126, 0xbfb8aa3b, v126
	v_exp_f32_e32 v126, v126
	v_log_f32_e32 v125, v125
	v_add_f32_e32 v126, 1.0, v126
	v_rcp_f32_e32 v126, v126
	v_mul_f32_e32 v124, 0x3f317217, v125
	v_fma_f32 v126, v187, v126, v16
	v_mul_f32_e32 v130, v113, v180
	v_mul_f32_e32 v130, 0xbfb8aa3b, v130
	v_log_f32_e32 v126, v126
	v_exp_f32_e32 v130, v130
	v_mov_b32_e32 v125, v124
	v_mul_f32_e32 v124, 0x3f317217, v126
	v_add_f32_e32 v130, 1.0, v130
	v_rcp_f32_e32 v130, v130
	v_cvt_pk_f16_f32 v125, v127, v125
	v_mov_b32_e32 v126, v124
	v_fma_f32 v124, v186, v130, v17
	v_mul_f32_e32 v130, v114, v180
	v_mul_f32_e32 v130, 0xbfb8aa3b, v130
	v_exp_f32_e32 v130, v130
	v_log_f32_e32 v124, v124
	v_add_f32_e32 v130, 1.0, v130
	v_rcp_f32_e32 v130, v130
	v_mul_f32_e32 v131, 0x3f317217, v124
	v_fma_f32 v130, v143, v130, v18
	v_mov_b32_e32 v124, v131
	v_mov_b32_e32 v132, v124
	v_cvt_pk_f16_f32 v126, v126, v132
	v_mul_f32_e32 v131, v115, v180
	v_mul_f32_e32 v131, 0xbfb8aa3b, v131
	v_exp_f32_e32 v131, v131
	v_log_f32_e32 v130, v130
	v_add_f32_e32 v131, 1.0, v131
	v_rcp_f32_e32 v131, v131
	v_mul_f32_e32 v124, 0x3f317217, v130
	v_fma_f32 v131, v142, v131, v19
	v_log_f32_e32 v131, v131
	v_mov_b32_e32 v130, v124
	v_mul_f32_e32 v124, 0x3f317217, v131
	v_mov_b32_e32 v131, v124
	v_cvt_pk_f16_f32 v124, v116, v121
	v_cvt_pk_f16_f32 v127, v130, v131
	global_store_dwordx4 v[128:129], v[124:127], off offset:256 nt

; __device__ __forceinline__ float sigmoidf_(float z) { return __builtin_amdgcn_rcpf(1.0f + __builtin_amdgcn_exp2f(-1.4426950408889634f * z)); }
; __device__ __forceinline__ u32x4 pack8(const float (&f)[8]) { u32x4 w; w.x = pk2(f[0], f[1]); w.y = pk2(f[2], f[3]); w.z = pk2(f[4], f[5]); w.w = pk2(f[6], f[7]); return w; }
;     __device__ __forceinline__ float compute(const Pre& p, f32x4 (&acc)[2][2][4][2], const f32x4 (&cv)[2][2], const pg8::Unit& u, int ai, int m, int wr, int wc, int fr, int fq) const {
;     ...
;             if (MODE == EM_PROJ) {
;                 const int pn = u.pn;
;                 if (pn < 16) {
;                     const int sec = pn >> 2, col = (pn & 3) * 256 + ct; const size_t o = (size_t)row * 1024 + col;
;                     if (sec == 0) { float w[8];
; #pragma unroll
;                         for (int j = 0; j < 8; ++j) w[j] = v[j] * rs;
;                         __builtin_nontemporal_store(pack8(w), (u32x4*)((bf16_t*)(ws + WS_Q) + o));
;                     } else if (sec == 1) {
;                         float lf[8];
; #pragma unroll
;                         for (int j = 0; j < 8; ++j) { const float lb = j < 4 ? cv[bj][0][j] : cv[bj][1][j - 4]; const float sg = sigmoidf_(v[j] * rs); lf[j] = __logf(lb + (1.f - lb) * sg); }
;                         u32x4 hw; hw.x = pkh2(lf[0], lf[1]); hw.y = pkh2(lf[2], lf[3]); hw.z = pkh2(lf[4], lf[5]); hw.w = pkh2(lf[6], lf[7]);
;                         __builtin_nontemporal_store(hw, (u32x4*)((_Float16*)out + o));
.LBB0_333:
	v_mul_f32_e32 v115, v109, v178
	v_mul_f32_e32 v115, 0xbfb8aa3b, v115
	v_add_f32_e32 v108, 1.0, v108
	v_exp_f32_e32 v115, v115
	v_rcp_f32_e32 v108, v108
	v_add_f32_e32 v115, 1.0, v115
	v_fma_f32 v108, v201, v108, v36
	v_rcp_f32_e32 v115, v115
	s_nop 0
	v_fma_f32 v115, v199, v115, v37
	v_log_f32_e32 v108, v108
	s_nop 0
	v_mul_f32_e32 v118, 0x3f317217, v108
	v_mul_f32_e32 v119, v110, v178
	v_mul_f32_e32 v119, 0xbfb8aa3b, v119
	v_log_f32_e32 v115, v115
	v_exp_f32_e32 v119, v119
	s_nop 0
	v_add_f32_e32 v119, 1.0, v119
	v_rcp_f32_e32 v119, v119
	v_mov_b32_e32 v108, v118
	v_mul_f32_e32 v118, 0x3f317217, v115
	v_mov_b32_e32 v115, v118
	v_fma_f32 v118, v198, v119, v38
	v_mul_f32_e32 v119, v111, v178
	v_mul_f32_e32 v119, 0xbfb8aa3b, v119
	v_exp_f32_e32 v119, v119
	v_log_f32_e32 v118, v118
	v_add_f32_e32 v119, 1.0, v119
	v_rcp_f32_e32 v119, v119
	v_mul_f32_e32 v120, 0x3f317217, v118
	v_fma_f32 v119, v197, v119, v39
	v_mov_b32_e32 v118, v120
	v_mov_b32_e32 v121, v118
	v_mul_f32_e32 v120, v104, v178
	v_mul_f32_e32 v120, 0xbfb8aa3b, v120
	v_exp_f32_e32 v120, v120
	v_log_f32_e32 v119, v119
	v_add_f32_e32 v120, 1.0, v120
	v_rcp_f32_e32 v120, v120
	v_mul_f32_e32 v118, 0x3f317217, v119
	v_fma_f32 v120, v196, v120, v32
	v_mul_f32_e32 v122, v105, v178
	v_mul_f32_e32 v122, 0xbfb8aa3b, v122
	v_log_f32_e32 v120, v120
	v_exp_f32_e32 v122, v122
	v_mov_b32_e32 v119, v118
	v_mul_f32_e32 v118, 0x3f317217, v120
	v_add_f32_e32 v122, 1.0, v122
	v_rcp_f32_e32 v122, v122
	v_cvt_pk_f16_f32 v119, v121, v119
	v_mov_b32_e32 v120, v118
	v_fma_f32 v118, v195, v122, v33
	v_mul_f32_e32 v122, v106, v178
	v_mul_f32_e32 v122, 0xbfb8aa3b, v122
	v_exp_f32_e32 v122, v122
	v_log_f32_e32 v118, v118
	v_add_f32_e32 v122, 1.0, v122
	v_rcp_f32_e32 v122, v122
	v_mul_f32_e32 v123, 0x3f317217, v118
	v_fma_f32 v122, v194, v122, v34
	v_mov_b32_e32 v118, v123
	v_mov_b32_e32 v124, v118
	v_cvt_pk_f16_f32 v120, v120, v124
	v_mul_f32_e32 v123, v107, v178
	v_mul_f32_e32 v123, 0xbfb8aa3b, v123
	v_exp_f32_e32 v123, v123
	v_log_f32_e32 v122, v122
	v_add_f32_e32 v123, 1.0, v123
	v_rcp_f32_e32 v123, v123
	v_mul_f32_e32 v118, 0x3f317217, v122
	v_fma_f32 v123, v193, v123, v35
	v_log_f32_e32 v123, v123
	v_mov_b32_e32 v122, v118
	v_mul_f32_e32 v118, 0x3f317217, v123
	v_mov_b32_e32 v123, v118
	v_cvt_pk_f16_f32 v118, v108, v115
	v_cvt_pk_f16_f32 v121, v122, v123
	v_lshl_add_u64 v[122:123], v[116:117], 1, s[70:71]
	global_store_dwordx4 v[122:123], v[118:121], off nt

; __device__ __forceinline__ float sigmoidf_(float z) { return __builtin_amdgcn_rcpf(1.0f + __builtin_amdgcn_exp2f(-1.4426950408889634f * z)); }
; __device__ __forceinline__ u32x4 pack8(const float (&f)[8]) { u32x4 w; w.x = pk2(f[0], f[1]); w.y = pk2(f[2], f[3]); w.z = pk2(f[4], f[5]); w.w = pk2(f[6], f[7]); return w; }
;     __device__ __forceinline__ float compute(const Pre& p, f32x4 (&acc)[2][2][4][2], const f32x4 (&cv)[2][2], const pg8::Unit& u, int ai, int m, int wr, int wc, int fr, int fq) const {
;     ...
;             if (MODE == EM_PROJ) {
;                 const int pn = u.pn;
;                 if (pn < 16) {
;                     const int sec = pn >> 2, col = (pn & 3) * 256 + ct; const size_t o = (size_t)row * 1024 + col;
;                     if (sec == 0) { float w[8];
; #pragma unroll
;                         for (int j = 0; j < 8; ++j) w[j] = v[j] * rs;
;                         __builtin_nontemporal_store(pack8(w), (u32x4*)((bf16_t*)(ws + WS_Q) + o));
;                     } else if (sec == 1) {
;                         float lf[8];
; #pragma unroll
;                         for (int j = 0; j < 8; ++j) { const float lb = j < 4 ? cv[bj][0][j] : cv[bj][1][j - 4]; const float sg = sigmoidf_(v[j] * rs); lf[j] = __logf(lb + (1.f - lb) * sg); }
;                         u32x4 hw; hw.x = pkh2(lf[0], lf[1]); hw.y = pkh2(lf[2], lf[3]); hw.z = pkh2(lf[4], lf[5]); hw.w = pkh2(lf[6], lf[7]);
;                         __builtin_nontemporal_store(hw, (u32x4*)((_Float16*)out + o));
.LBB0_349:
	v_mul_f32_e32 v105, v101, v178
	v_mul_f32_e32 v105, 0xbfb8aa3b, v105
	v_add_f32_e32 v100, 1.0, v100
	v_exp_f32_e32 v105, v105
	v_rcp_f32_e32 v100, v100
	v_lshl_add_u64 v[112:113], v[112:113], 0, v[168:169]
	v_lshl_add_u64 v[112:113], v[112:113], 1, s[70:71]
	v_add_f32_e32 v105, 1.0, v105
	v_fma_f32 v100, v202, v100, v20
	v_rcp_f32_e32 v105, v105
	s_nop 0
	v_fma_f32 v105, v200, v105, v21
	v_log_f32_e32 v100, v100
	s_nop 0
	v_mul_f32_e32 v108, 0x3f317217, v100
	v_mul_f32_e32 v109, v102, v178
	v_mul_f32_e32 v109, 0xbfb8aa3b, v109
	v_log_f32_e32 v105, v105
	v_exp_f32_e32 v109, v109
	s_nop 0
	v_add_f32_e32 v109, 1.0, v109
	v_rcp_f32_e32 v109, v109
	v_mov_b32_e32 v100, v108
	v_mul_f32_e32 v108, 0x3f317217, v105
	v_mov_b32_e32 v105, v108
	v_fma_f32 v108, v189, v109, v22
	v_mul_f32_e32 v109, v103, v178
	v_mul_f32_e32 v109, 0xbfb8aa3b, v109
	v_exp_f32_e32 v109, v109
	v_log_f32_e32 v108, v108
	v_add_f32_e32 v109, 1.0, v109
	v_rcp_f32_e32 v109, v109
	v_mul_f32_e32 v110, 0x3f317217, v108
	v_fma_f32 v109, v188, v109, v23
	v_mov_b32_e32 v108, v110
	v_mov_b32_e32 v111, v108
	v_mul_f32_e32 v110, v96, v178
	v_mul_f32_e32 v110, 0xbfb8aa3b, v110
	v_exp_f32_e32 v110, v110
	v_log_f32_e32 v109, v109
	v_add_f32_e32 v110, 1.0, v110
	v_rcp_f32_e32 v110, v110
	v_mul_f32_e32 v108, 0x3f317217, v109
	v_fma_f32 v110, v187, v110, v16
	v_mul_f32_e32 v114, v97, v178
	v_mul_f32_e32 v114, 0xbfb8aa3b, v114
	v_log_f32_e32 v110, v110
	v_exp_f32_e32 v114, v114
	v_mov_b32_e32 v109, v108
	v_mul_f32_e32 v108, 0x3f317217, v110
	v_add_f32_e32 v114, 1.0, v114
	v_rcp_f32_e32 v114, v114
	v_cvt_pk_f16_f32 v109, v111, v109
	v_mov_b32_e32 v110, v108
	v_fma_f32 v108, v186, v114, v17
	v_mul_f32_e32 v114, v98, v178
	v_mul_f32_e32 v114, 0xbfb8aa3b, v114
	v_exp_f32_e32 v114, v114
	v_log_f32_e32 v108, v108
	v_add_f32_e32 v114, 1.0, v114
	v_rcp_f32_e32 v114, v114
	v_mul_f32_e32 v115, 0x3f317217, v108
	v_fma_f32 v114, v143, v114, v18
	v_mov_b32_e32 v108, v115
	v_mov_b32_e32 v116, v108
	v_cvt_pk_f16_f32 v110, v110, v116
	v_mul_f32_e32 v115, v99, v178
	v_mul_f32_e32 v115, 0xbfb8aa3b, v115
	v_exp_f32_e32 v115, v115
	v_log_f32_e32 v114, v114
	v_add_f32_e32 v115, 1.0, v115
	v_rcp_f32_e32 v115, v115
	v_mul_f32_e32 v108, 0x3f317217, v114
	v_fma_f32 v115, v142, v115, v19
	v_log_f32_e32 v115, v115
	v_mov_b32_e32 v114, v108
	v_mul_f32_e32 v108, 0x3f317217, v115
	v_mov_b32_e32 v115, v108
	v_cvt_pk_f16_f32 v108, v100, v105
	v_cvt_pk_f16_f32 v111, v114, v115
	global_store_dwordx4 v[112:113], v[108:111], off offset:256 nt

; __device__ __forceinline__ float sigmoidf_(float z) { return __builtin_amdgcn_rcpf(1.0f + __builtin_amdgcn_exp2f(-1.4426950408889634f * z)); }
; __device__ __forceinline__ u32x4 pack8(const float (&f)[8]) { u32x4 w; w.x = pk2(f[0], f[1]); w.y = pk2(f[2], f[3]); w.z = pk2(f[4], f[5]); w.w = pk2(f[6], f[7]); return w; }
;     __device__ __forceinline__ float compute(const Pre& p, f32x4 (&acc)[2][2][4][2], const f32x4 (&cv)[2][2], const pg8::Unit& u, int ai, int m, int wr, int wc, int fr, int fq) const {
;     ...
;             if (MODE == EM_PROJ) {
;                 const int pn = u.pn;
;                 if (pn < 16) {
;                     const int sec = pn >> 2, col = (pn & 3) * 256 + ct; const size_t o = (size_t)row * 1024 + col;
;                     if (sec == 0) { float w[8];
; #pragma unroll
;                         for (int j = 0; j < 8; ++j) w[j] = v[j] * rs;
;                         __builtin_nontemporal_store(pack8(w), (u32x4*)((bf16_t*)(ws + WS_Q) + o));
;                     } else if (sec == 1) {
;                         float lf[8];
; #pragma unroll
;                         for (int j = 0; j < 8; ++j) { const float lb = j < 4 ? cv[bj][0][j] : cv[bj][1][j - 4]; const float sg = sigmoidf_(v[j] * rs); lf[j] = __logf(lb + (1.f - lb) * sg); }
;                         u32x4 hw; hw.x = pkh2(lf[0], lf[1]); hw.y = pkh2(lf[2], lf[3]); hw.z = pkh2(lf[4], lf[5]); hw.w = pkh2(lf[6], lf[7]);
;                         __builtin_nontemporal_store(hw, (u32x4*)((_Float16*)out + o));
.LBB0_365:
	v_mul_f32_e32 v99, v93, v176
	v_mul_f32_e32 v99, 0xbfb8aa3b, v99
	v_add_f32_e32 v92, 1.0, v92
	v_exp_f32_e32 v99, v99
	v_rcp_f32_e32 v92, v92
	v_add_f32_e32 v99, 1.0, v99
	v_fma_f32 v92, v201, v92, v36
	v_rcp_f32_e32 v99, v99
	s_nop 0
	v_fma_f32 v99, v199, v99, v37
	v_log_f32_e32 v92, v92
	s_nop 0
	v_mul_f32_e32 v102, 0x3f317217, v92
	v_mul_f32_e32 v103, v94, v176
	v_mul_f32_e32 v103, 0xbfb8aa3b, v103
	v_log_f32_e32 v99, v99
	v_exp_f32_e32 v103, v103
	s_nop 0
	v_add_f32_e32 v103, 1.0, v103
	v_rcp_f32_e32 v103, v103
	v_mov_b32_e32 v92, v102
	v_mul_f32_e32 v102, 0x3f317217, v99
	v_mov_b32_e32 v99, v102
	v_fma_f32 v102, v198, v103, v38
	v_mul_f32_e32 v103, v95, v176
	v_mul_f32_e32 v103, 0xbfb8aa3b, v103
	v_exp_f32_e32 v103, v103
	v_log_f32_e32 v102, v102
	v_add_f32_e32 v103, 1.0, v103
	v_rcp_f32_e32 v103, v103
	v_mul_f32_e32 v104, 0x3f317217, v102
	v_fma_f32 v103, v197, v103, v39
	v_mov_b32_e32 v102, v104
	v_mov_b32_e32 v105, v102
	v_mul_f32_e32 v104, v88, v176
	v_mul_f32_e32 v104, 0xbfb8aa3b, v104
	v_exp_f32_e32 v104, v104
	v_log_f32_e32 v103, v103
	v_add_f32_e32 v104, 1.0, v104
	v_rcp_f32_e32 v104, v104
	v_mul_f32_e32 v102, 0x3f317217, v103
	v_fma_f32 v104, v196, v104, v32
	v_mul_f32_e32 v106, v89, v176
	v_mul_f32_e32 v106, 0xbfb8aa3b, v106
	v_log_f32_e32 v104, v104
	v_exp_f32_e32 v106, v106
	v_mov_b32_e32 v103, v102
	v_mul_f32_e32 v102, 0x3f317217, v104
	v_add_f32_e32 v106, 1.0, v106
	v_rcp_f32_e32 v106, v106
	v_cvt_pk_f16_f32 v103, v105, v103
	v_mov_b32_e32 v104, v102
	v_fma_f32 v102, v195, v106, v33
	v_mul_f32_e32 v106, v90, v176
	v_mul_f32_e32 v106, 0xbfb8aa3b, v106
	v_exp_f32_e32 v106, v106
	v_log_f32_e32 v102, v102
	v_add_f32_e32 v106, 1.0, v106
	v_rcp_f32_e32 v106, v106
	v_mul_f32_e32 v107, 0x3f317217, v102
	v_fma_f32 v106, v194, v106, v34
	v_mov_b32_e32 v102, v107
	v_mov_b32_e32 v108, v102
	v_cvt_pk_f16_f32 v104, v104, v108
	v_mul_f32_e32 v107, v91, v176
	v_mul_f32_e32 v107, 0xbfb8aa3b, v107
	v_exp_f32_e32 v107, v107
	v_log_f32_e32 v106, v106
	v_add_f32_e32 v107, 1.0, v107
	v_rcp_f32_e32 v107, v107
	v_mul_f32_e32 v102, 0x3f317217, v106
	v_fma_f32 v107, v193, v107, v35
	v_log_f32_e32 v107, v107
	v_mov_b32_e32 v106, v102
	v_mul_f32_e32 v102, 0x3f317217, v107
	v_mov_b32_e32 v107, v102
	v_cvt_pk_f16_f32 v102, v92, v99
	v_cvt_pk_f16_f32 v105, v106, v107
	v_lshl_add_u64 v[106:107], v[100:101], 1, s[70:71]
	global_store_dwordx4 v[106:107], v[102:105], off nt

; __device__ __forceinline__ float sigmoidf_(float z) { return __builtin_amdgcn_rcpf(1.0f + __builtin_amdgcn_exp2f(-1.4426950408889634f * z)); }
; __device__ __forceinline__ u32x4 pack8(const float (&f)[8]) { u32x4 w; w.x = pk2(f[0], f[1]); w.y = pk2(f[2], f[3]); w.z = pk2(f[4], f[5]); w.w = pk2(f[6], f[7]); return w; }
;     __device__ __forceinline__ float compute(const Pre& p, f32x4 (&acc)[2][2][4][2], const f32x4 (&cv)[2][2], const pg8::Unit& u, int ai, int m, int wr, int wc, int fr, int fq) const {
;     ...
;             if (MODE == EM_PROJ) {
;                 const int pn = u.pn;
;                 if (pn < 16) {
;                     const int sec = pn >> 2, col = (pn & 3) * 256 + ct; const size_t o = (size_t)row * 1024 + col;
;                     if (sec == 0) { float w[8];
; #pragma unroll
;                         for (int j = 0; j < 8; ++j) w[j] = v[j] * rs;
;                         __builtin_nontemporal_store(pack8(w), (u32x4*)((bf16_t*)(ws + WS_Q) + o));
;                     } else if (sec == 1) {
;                         float lf[8];
; #pragma unroll
;                         for (int j = 0; j < 8; ++j) { const float lb = j < 4 ? cv[bj][0][j] : cv[bj][1][j - 4]; const float sg = sigmoidf_(v[j] * rs); lf[j] = __logf(lb + (1.f - lb) * sg); }
;                         u32x4 hw; hw.x = pkh2(lf[0], lf[1]); hw.y = pkh2(lf[2], lf[3]); hw.z = pkh2(lf[4], lf[5]); hw.w = pkh2(lf[6], lf[7]);
;                         __builtin_nontemporal_store(hw, (u32x4*)((_Float16*)out + o));
.LBB0_381:
	v_mul_f32_e32 v89, v85, v176
	v_mul_f32_e32 v89, 0xbfb8aa3b, v89
	v_add_f32_e32 v84, 1.0, v84
	v_exp_f32_e32 v89, v89
	v_rcp_f32_e32 v84, v84
	v_lshl_add_u64 v[96:97], v[96:97], 0, v[168:169]
	v_lshl_add_u64 v[96:97], v[96:97], 1, s[70:71]
	v_add_f32_e32 v89, 1.0, v89
	v_fma_f32 v84, v202, v84, v20
	v_rcp_f32_e32 v89, v89
	s_nop 0
	v_fma_f32 v89, v200, v89, v21
	v_log_f32_e32 v84, v84
	s_nop 0
	v_mul_f32_e32 v92, 0x3f317217, v84
	v_mul_f32_e32 v93, v86, v176
	v_mul_f32_e32 v93, 0xbfb8aa3b, v93
	v_log_f32_e32 v89, v89
	v_exp_f32_e32 v93, v93
	s_nop 0
	v_add_f32_e32 v93, 1.0, v93
	v_rcp_f32_e32 v93, v93
	v_mov_b32_e32 v84, v92
	v_mul_f32_e32 v92, 0x3f317217, v89
	v_mov_b32_e32 v89, v92
	v_fma_f32 v92, v189, v93, v22
	v_mul_f32_e32 v93, v87, v176
	v_mul_f32_e32 v93, 0xbfb8aa3b, v93
	v_exp_f32_e32 v93, v93
	v_log_f32_e32 v92, v92
	v_add_f32_e32 v93, 1.0, v93
	v_rcp_f32_e32 v93, v93
	v_mul_f32_e32 v94, 0x3f317217, v92
	v_fma_f32 v93, v188, v93, v23
	v_mov_b32_e32 v92, v94
	v_mov_b32_e32 v95, v92
	v_mul_f32_e32 v94, v80, v176
	v_mul_f32_e32 v94, 0xbfb8aa3b, v94
	v_exp_f32_e32 v94, v94
	v_log_f32_e32 v93, v93
	v_add_f32_e32 v94, 1.0, v94
	v_rcp_f32_e32 v94, v94
	v_mul_f32_e32 v92, 0x3f317217, v93
	v_fma_f32 v94, v187, v94, v16
	v_mul_f32_e32 v98, v81, v176
	v_mul_f32_e32 v98, 0xbfb8aa3b, v98
	v_log_f32_e32 v94, v94
	v_exp_f32_e32 v98, v98
	v_mov_b32_e32 v93, v92
	v_mul_f32_e32 v92, 0x3f317217, v94
	v_add_f32_e32 v98, 1.0, v98
	v_rcp_f32_e32 v98, v98
	v_cvt_pk_f16_f32 v93, v95, v93
	v_mov_b32_e32 v94, v92
	v_fma_f32 v92, v186, v98, v17
	v_mul_f32_e32 v98, v82, v176
	v_mul_f32_e32 v98, 0xbfb8aa3b, v98
	v_exp_f32_e32 v98, v98
	v_log_f32_e32 v92, v92
	v_add_f32_e32 v98, 1.0, v98
	v_rcp_f32_e32 v98, v98
	v_mul_f32_e32 v99, 0x3f317217, v92
	v_fma_f32 v98, v143, v98, v18
	v_mov_b32_e32 v92, v99
	v_mov_b32_e32 v100, v92
	v_cvt_pk_f16_f32 v94, v94, v100
	v_mul_f32_e32 v99, v83, v176
	v_mul_f32_e32 v99, 0xbfb8aa3b, v99
	v_exp_f32_e32 v99, v99
	v_log_f32_e32 v98, v98
	v_add_f32_e32 v99, 1.0, v99
	v_rcp_f32_e32 v99, v99
	v_mul_f32_e32 v92, 0x3f317217, v98
	v_fma_f32 v99, v142, v99, v19
	v_log_f32_e32 v99, v99
	v_mov_b32_e32 v98, v92
	v_mul_f32_e32 v92, 0x3f317217, v99
	v_mov_b32_e32 v99, v92
	v_cvt_pk_f16_f32 v92, v84, v89
	v_cvt_pk_f16_f32 v95, v98, v99
	global_store_dwordx4 v[96:97], v[92:95], off offset:256 nt

; __device__ __forceinline__ float sigmoidf_(float z) { return __builtin_amdgcn_rcpf(1.0f + __builtin_amdgcn_exp2f(-1.4426950408889634f * z)); }
; __device__ __forceinline__ u32x4 pack8(const float (&f)[8]) { u32x4 w; w.x = pk2(f[0], f[1]); w.y = pk2(f[2], f[3]); w.z = pk2(f[4], f[5]); w.w = pk2(f[6], f[7]); return w; }
;     __device__ __forceinline__ float compute(const Pre& p, f32x4 (&acc)[2][2][4][2], const f32x4 (&cv)[2][2], const pg8::Unit& u, int ai, int m, int wr, int wc, int fr, int fq) const {
;     ...
;             if (MODE == EM_PROJ) {
;                 const int pn = u.pn;
;                 if (pn < 16) {
;                     const int sec = pn >> 2, col = (pn & 3) * 256 + ct; const size_t o = (size_t)row * 1024 + col;
;                     if (sec == 0) { float w[8];
; #pragma unroll
;                         for (int j = 0; j < 8; ++j) w[j] = v[j] * rs;
;                         __builtin_nontemporal_store(pack8(w), (u32x4*)((bf16_t*)(ws + WS_Q) + o));
;                     } else if (sec == 1) {
;                         float lf[8];
; #pragma unroll
;                         for (int j = 0; j < 8; ++j) { const float lb = j < 4 ? cv[bj][0][j] : cv[bj][1][j - 4]; const float sg = sigmoidf_(v[j] * rs); lf[j] = __logf(lb + (1.f - lb) * sg); }
;                         u32x4 hw; hw.x = pkh2(lf[0], lf[1]); hw.y = pkh2(lf[2], lf[3]); hw.z = pkh2(lf[4], lf[5]); hw.w = pkh2(lf[6], lf[7]);
;                         __builtin_nontemporal_store(hw, (u32x4*)((_Float16*)out + o));
.LBB0_397:
	v_mul_f32_e32 v83, v77, v174
	v_mul_f32_e32 v83, 0xbfb8aa3b, v83
	v_add_f32_e32 v76, 1.0, v76
	v_exp_f32_e32 v83, v83
	v_rcp_f32_e32 v76, v76
	v_add_f32_e32 v83, 1.0, v83
	v_fma_f32 v76, v201, v76, v36
	v_rcp_f32_e32 v83, v83
	s_nop 0
	v_fma_f32 v83, v199, v83, v37
	v_log_f32_e32 v76, v76
	s_nop 0
	v_mul_f32_e32 v86, 0x3f317217, v76
	v_mul_f32_e32 v87, v78, v174
	v_mul_f32_e32 v87, 0xbfb8aa3b, v87
	v_log_f32_e32 v83, v83
	v_exp_f32_e32 v87, v87
	s_nop 0
	v_add_f32_e32 v87, 1.0, v87
	v_rcp_f32_e32 v87, v87
	v_mov_b32_e32 v76, v86
	v_mul_f32_e32 v86, 0x3f317217, v83
	v_mov_b32_e32 v83, v86
	v_fma_f32 v86, v198, v87, v38
	v_mul_f32_e32 v87, v79, v174
	v_mul_f32_e32 v87, 0xbfb8aa3b, v87
	v_exp_f32_e32 v87, v87
	v_log_f32_e32 v86, v86
	v_add_f32_e32 v87, 1.0, v87
	v_rcp_f32_e32 v87, v87
	v_mul_f32_e32 v88, 0x3f317217, v86
	v_fma_f32 v87, v197, v87, v39
	v_mov_b32_e32 v86, v88
	v_mov_b32_e32 v89, v86
	v_mul_f32_e32 v88, v72, v174
	v_mul_f32_e32 v88, 0xbfb8aa3b, v88
	v_exp_f32_e32 v88, v88
	v_log_f32_e32 v87, v87
	v_add_f32_e32 v88, 1.0, v88
	v_rcp_f32_e32 v88, v88
	v_mul_f32_e32 v86, 0x3f317217, v87
	v_fma_f32 v88, v196, v88, v32
	v_mul_f32_e32 v90, v73, v174
	v_mul_f32_e32 v90, 0xbfb8aa3b, v90
	v_log_f32_e32 v88, v88
	v_exp_f32_e32 v90, v90
	v_mov_b32_e32 v87, v86
	v_mul_f32_e32 v86, 0x3f317217, v88
	v_add_f32_e32 v90, 1.0, v90
	v_rcp_f32_e32 v90, v90
	v_cvt_pk_f16_f32 v87, v89, v87
	v_mov_b32_e32 v88, v86
	v_fma_f32 v86, v195, v90, v33
	v_mul_f32_e32 v90, v74, v174
	v_mul_f32_e32 v90, 0xbfb8aa3b, v90
	v_exp_f32_e32 v90, v90
	v_log_f32_e32 v86, v86
	v_add_f32_e32 v90, 1.0, v90
	v_rcp_f32_e32 v90, v90
	v_mul_f32_e32 v91, 0x3f317217, v86
	v_fma_f32 v90, v194, v90, v34
	v_mov_b32_e32 v86, v91
	v_mov_b32_e32 v92, v86
	v_cvt_pk_f16_f32 v88, v88, v92
	v_mul_f32_e32 v91, v75, v174
	v_mul_f32_e32 v91, 0xbfb8aa3b, v91
	v_exp_f32_e32 v91, v91
	v_log_f32_e32 v90, v90
	v_add_f32_e32 v91, 1.0, v91
	v_rcp_f32_e32 v91, v91
	v_mul_f32_e32 v86, 0x3f317217, v90
	v_fma_f32 v91, v193, v91, v35
	v_log_f32_e32 v91, v91
	v_mov_b32_e32 v90, v86
	v_mul_f32_e32 v86, 0x3f317217, v91
	v_mov_b32_e32 v91, v86
	v_cvt_pk_f16_f32 v86, v76, v83
	v_cvt_pk_f16_f32 v89, v90, v91
	v_lshl_add_u64 v[90:91], v[84:85], 1, s[70:71]
	global_store_dwordx4 v[90:91], v[86:89], off nt

; __device__ __forceinline__ float sigmoidf_(float z) { return __builtin_amdgcn_rcpf(1.0f + __builtin_amdgcn_exp2f(-1.4426950408889634f * z)); }
; __device__ __forceinline__ u32x4 pack8(const float (&f)[8]) { u32x4 w; w.x = pk2(f[0], f[1]); w.y = pk2(f[2], f[3]); w.z = pk2(f[4], f[5]); w.w = pk2(f[6], f[7]); return w; }
;     __device__ __forceinline__ float compute(const Pre& p, f32x4 (&acc)[2][2][4][2], const f32x4 (&cv)[2][2], const pg8::Unit& u, int ai, int m, int wr, int wc, int fr, int fq) const {
;     ...
;             if (MODE == EM_PROJ) {
;                 const int pn = u.pn;
;                 if (pn < 16) {
;                     const int sec = pn >> 2, col = (pn & 3) * 256 + ct; const size_t o = (size_t)row * 1024 + col;
;                     if (sec == 0) { float w[8];
; #pragma unroll
;                         for (int j = 0; j < 8; ++j) w[j] = v[j] * rs;
;                         __builtin_nontemporal_store(pack8(w), (u32x4*)((bf16_t*)(ws + WS_Q) + o));
;                     } else if (sec == 1) {
;                         float lf[8];
; #pragma unroll
;                         for (int j = 0; j < 8; ++j) { const float lb = j < 4 ? cv[bj][0][j] : cv[bj][1][j - 4]; const float sg = sigmoidf_(v[j] * rs); lf[j] = __logf(lb + (1.f - lb) * sg); }
;                         u32x4 hw; hw.x = pkh2(lf[0], lf[1]); hw.y = pkh2(lf[2], lf[3]); hw.z = pkh2(lf[4], lf[5]); hw.w = pkh2(lf[6], lf[7]);
;                         __builtin_nontemporal_store(hw, (u32x4*)((_Float16*)out + o));
.LBB0_413:
	v_mul_f32_e32 v73, v69, v174
	v_mul_f32_e32 v73, 0xbfb8aa3b, v73
	v_add_f32_e32 v68, 1.0, v68
	v_exp_f32_e32 v73, v73
	v_rcp_f32_e32 v68, v68
	v_lshl_add_u64 v[80:81], v[80:81], 0, v[168:169]
	v_lshl_add_u64 v[80:81], v[80:81], 1, s[70:71]
	v_add_f32_e32 v73, 1.0, v73
	v_fma_f32 v68, v202, v68, v20
	v_rcp_f32_e32 v73, v73
	s_nop 0
	v_fma_f32 v73, v200, v73, v21
	v_log_f32_e32 v68, v68
	s_nop 0
	v_mul_f32_e32 v76, 0x3f317217, v68
	v_mul_f32_e32 v77, v70, v174
	v_mul_f32_e32 v77, 0xbfb8aa3b, v77
	v_log_f32_e32 v73, v73
	v_exp_f32_e32 v77, v77
	s_nop 0
	v_add_f32_e32 v77, 1.0, v77
	v_rcp_f32_e32 v77, v77
	v_mov_b32_e32 v68, v76
	v_mul_f32_e32 v76, 0x3f317217, v73
	v_mov_b32_e32 v73, v76
	v_fma_f32 v76, v189, v77, v22
	v_mul_f32_e32 v77, v71, v174
	v_mul_f32_e32 v77, 0xbfb8aa3b, v77
	v_exp_f32_e32 v77, v77
	v_log_f32_e32 v76, v76
	v_add_f32_e32 v77, 1.0, v77
	v_rcp_f32_e32 v77, v77
	v_mul_f32_e32 v78, 0x3f317217, v76
	v_fma_f32 v77, v188, v77, v23
	v_mov_b32_e32 v76, v78
	v_mov_b32_e32 v79, v76
	v_mul_f32_e32 v78, v64, v174
	v_mul_f32_e32 v78, 0xbfb8aa3b, v78
	v_exp_f32_e32 v78, v78
	v_log_f32_e32 v77, v77
	v_add_f32_e32 v78, 1.0, v78
	v_rcp_f32_e32 v78, v78
	v_mul_f32_e32 v76, 0x3f317217, v77
	v_fma_f32 v78, v187, v78, v16
	v_mul_f32_e32 v82, v65, v174
	v_mul_f32_e32 v82, 0xbfb8aa3b, v82
	v_log_f32_e32 v78, v78
	v_exp_f32_e32 v82, v82
	v_mov_b32_e32 v77, v76
	v_mul_f32_e32 v76, 0x3f317217, v78
	v_add_f32_e32 v82, 1.0, v82
	v_rcp_f32_e32 v82, v82
	v_cvt_pk_f16_f32 v77, v79, v77
	v_mov_b32_e32 v78, v76
	v_fma_f32 v76, v186, v82, v17
	v_mul_f32_e32 v82, v66, v174
	v_mul_f32_e32 v82, 0xbfb8aa3b, v82
	v_exp_f32_e32 v82, v82
	v_log_f32_e32 v76, v76
	v_add_f32_e32 v82, 1.0, v82
	v_rcp_f32_e32 v82, v82
	v_mul_f32_e32 v83, 0x3f317217, v76
	v_fma_f32 v82, v143, v82, v18
	v_mov_b32_e32 v76, v83
	v_mov_b32_e32 v84, v76
	v_cvt_pk_f16_f32 v78, v78, v84
	v_mul_f32_e32 v83, v67, v174
	v_mul_f32_e32 v83, 0xbfb8aa3b, v83
	v_exp_f32_e32 v83, v83
	v_log_f32_e32 v82, v82
	v_add_f32_e32 v83, 1.0, v83
	v_rcp_f32_e32 v83, v83
	v_mul_f32_e32 v76, 0x3f317217, v82
	v_fma_f32 v83, v142, v83, v19
	v_log_f32_e32 v83, v83
	v_mov_b32_e32 v82, v76
	v_mul_f32_e32 v76, 0x3f317217, v83
	v_mov_b32_e32 v83, v76
	v_cvt_pk_f16_f32 v76, v68, v73
	v_cvt_pk_f16_f32 v79, v82, v83
	global_store_dwordx4 v[80:81], v[76:79], off offset:256 nt

; __device__ __forceinline__ float sigmoidf_(float z) { return __builtin_amdgcn_rcpf(1.0f + __builtin_amdgcn_exp2f(-1.4426950408889634f * z)); }
; __device__ __forceinline__ u32x4 pack8(const float (&f)[8]) { u32x4 w; w.x = pk2(f[0], f[1]); w.y = pk2(f[2], f[3]); w.z = pk2(f[4], f[5]); w.w = pk2(f[6], f[7]); return w; }
;     __device__ __forceinline__ float compute(const Pre& p, f32x4 (&acc)[2][2][4][2], const f32x4 (&cv)[2][2], const pg8::Unit& u, int ai, int m, int wr, int wc, int fr, int fq) const {
;     ...
;             if (MODE == EM_PROJ) {
;                 const int pn = u.pn;
;                 if (pn < 16) {
;                     const int sec = pn >> 2, col = (pn & 3) * 256 + ct; const size_t o = (size_t)row * 1024 + col;
;                     if (sec == 0) { float w[8];
; #pragma unroll
;                         for (int j = 0; j < 8; ++j) w[j] = v[j] * rs;
;                         __builtin_nontemporal_store(pack8(w), (u32x4*)((bf16_t*)(ws + WS_Q) + o));
;                     } else if (sec == 1) {
;                         float lf[8];
; #pragma unroll
;                         for (int j = 0; j < 8; ++j) { const float lb = j < 4 ? cv[bj][0][j] : cv[bj][1][j - 4]; const float sg = sigmoidf_(v[j] * rs); lf[j] = __logf(lb + (1.f - lb) * sg); }
;                         u32x4 hw; hw.x = pkh2(lf[0], lf[1]); hw.y = pkh2(lf[2], lf[3]); hw.z = pkh2(lf[4], lf[5]); hw.w = pkh2(lf[6], lf[7]);
;                         __builtin_nontemporal_store(hw, (u32x4*)((_Float16*)out + o));
.LBB0_429:
	v_mul_f32_e32 v67, v61, v172
	v_mul_f32_e32 v67, 0xbfb8aa3b, v67
	v_add_f32_e32 v60, 1.0, v60
	v_exp_f32_e32 v67, v67
	v_rcp_f32_e32 v60, v60
	v_add_f32_e32 v67, 1.0, v67
	v_fma_f32 v60, v201, v60, v36
	v_rcp_f32_e32 v67, v67
	s_nop 0
	v_fma_f32 v67, v199, v67, v37
	v_log_f32_e32 v60, v60
	s_nop 0
	v_mul_f32_e32 v70, 0x3f317217, v60
	v_mul_f32_e32 v71, v62, v172
	v_mul_f32_e32 v71, 0xbfb8aa3b, v71
	v_log_f32_e32 v67, v67
	v_exp_f32_e32 v71, v71
	s_nop 0
	v_add_f32_e32 v71, 1.0, v71
	v_rcp_f32_e32 v71, v71
	v_mov_b32_e32 v60, v70
	v_mul_f32_e32 v70, 0x3f317217, v67
	v_mov_b32_e32 v67, v70
	v_fma_f32 v70, v198, v71, v38
	v_mul_f32_e32 v71, v63, v172
	v_mul_f32_e32 v71, 0xbfb8aa3b, v71
	v_exp_f32_e32 v71, v71
	v_log_f32_e32 v70, v70
	v_add_f32_e32 v71, 1.0, v71
	v_rcp_f32_e32 v71, v71
	v_mul_f32_e32 v72, 0x3f317217, v70
	v_fma_f32 v71, v197, v71, v39
	v_mov_b32_e32 v70, v72
	v_mov_b32_e32 v73, v70
	v_mul_f32_e32 v72, v56, v172
	v_mul_f32_e32 v72, 0xbfb8aa3b, v72
	v_exp_f32_e32 v72, v72
	v_log_f32_e32 v71, v71
	v_add_f32_e32 v72, 1.0, v72
	v_rcp_f32_e32 v72, v72
	v_mul_f32_e32 v70, 0x3f317217, v71
	v_fma_f32 v72, v196, v72, v32
	v_mul_f32_e32 v74, v57, v172
	v_mul_f32_e32 v74, 0xbfb8aa3b, v74
	v_log_f32_e32 v72, v72
	v_exp_f32_e32 v74, v74
	v_mov_b32_e32 v71, v70
	v_mul_f32_e32 v70, 0x3f317217, v72
	v_add_f32_e32 v74, 1.0, v74
	v_rcp_f32_e32 v74, v74
	v_cvt_pk_f16_f32 v71, v73, v71
	v_mov_b32_e32 v72, v70
	v_fma_f32 v70, v195, v74, v33
	v_mul_f32_e32 v74, v58, v172
	v_mul_f32_e32 v74, 0xbfb8aa3b, v74
	v_exp_f32_e32 v74, v74
	v_log_f32_e32 v70, v70
	v_add_f32_e32 v74, 1.0, v74
	v_rcp_f32_e32 v74, v74
	v_mul_f32_e32 v75, 0x3f317217, v70
	v_fma_f32 v74, v194, v74, v34
	v_mov_b32_e32 v70, v75
	v_mov_b32_e32 v76, v70
	v_cvt_pk_f16_f32 v72, v72, v76
	v_mul_f32_e32 v75, v59, v172
	v_mul_f32_e32 v75, 0xbfb8aa3b, v75
	v_exp_f32_e32 v75, v75
	v_log_f32_e32 v74, v74
	v_add_f32_e32 v75, 1.0, v75
	v_rcp_f32_e32 v75, v75
	v_mul_f32_e32 v70, 0x3f317217, v74
	v_fma_f32 v75, v193, v75, v35
	v_log_f32_e32 v75, v75
	v_mov_b32_e32 v74, v70
	v_mul_f32_e32 v70, 0x3f317217, v75
	v_mov_b32_e32 v75, v70
	v_cvt_pk_f16_f32 v70, v60, v67
	v_cvt_pk_f16_f32 v73, v74, v75
	v_lshl_add_u64 v[74:75], v[68:69], 1, s[70:71]
	global_store_dwordx4 v[74:75], v[70:73], off nt

; __device__ __forceinline__ float sigmoidf_(float z) { return __builtin_amdgcn_rcpf(1.0f + __builtin_amdgcn_exp2f(-1.4426950408889634f * z)); }
; __device__ __forceinline__ u32x4 pack8(const float (&f)[8]) { u32x4 w; w.x = pk2(f[0], f[1]); w.y = pk2(f[2], f[3]); w.z = pk2(f[4], f[5]); w.w = pk2(f[6], f[7]); return w; }
;     __device__ __forceinline__ float compute(const Pre& p, f32x4 (&acc)[2][2][4][2], const f32x4 (&cv)[2][2], const pg8::Unit& u, int ai, int m, int wr, int wc, int fr, int fq) const {
;     ...
;             if (MODE == EM_PROJ) {
;                 const int pn = u.pn;
;                 if (pn < 16) {
;                     const int sec = pn >> 2, col = (pn & 3) * 256 + ct; const size_t o = (size_t)row * 1024 + col;
;                     if (sec == 0) { float w[8];
; #pragma unroll
;                         for (int j = 0; j < 8; ++j) w[j] = v[j] * rs;
;                         __builtin_nontemporal_store(pack8(w), (u32x4*)((bf16_t*)(ws + WS_Q) + o));
;                     } else if (sec == 1) {
;                         float lf[8];
; #pragma unroll
;                         for (int j = 0; j < 8; ++j) { const float lb = j < 4 ? cv[bj][0][j] : cv[bj][1][j - 4]; const float sg = sigmoidf_(v[j] * rs); lf[j] = __logf(lb + (1.f - lb) * sg); }
;                         u32x4 hw; hw.x = pkh2(lf[0], lf[1]); hw.y = pkh2(lf[2], lf[3]); hw.z = pkh2(lf[4], lf[5]); hw.w = pkh2(lf[6], lf[7]);
;                         __builtin_nontemporal_store(hw, (u32x4*)((_Float16*)out + o));
.LBB0_445:
	v_mul_f32_e32 v57, v53, v172
	v_mul_f32_e32 v57, 0xbfb8aa3b, v57
	v_add_f32_e32 v52, 1.0, v52
	v_exp_f32_e32 v57, v57
	v_rcp_f32_e32 v52, v52
	v_lshl_add_u64 v[64:65], v[64:65], 0, v[168:169]
	v_lshl_add_u64 v[64:65], v[64:65], 1, s[70:71]
	v_add_f32_e32 v57, 1.0, v57
	v_fma_f32 v52, v202, v52, v20
	v_rcp_f32_e32 v57, v57
	s_nop 0
	v_fma_f32 v57, v200, v57, v21
	v_log_f32_e32 v52, v52
	s_nop 0
	v_mul_f32_e32 v60, 0x3f317217, v52
	v_mul_f32_e32 v61, v54, v172
	v_mul_f32_e32 v61, 0xbfb8aa3b, v61
	v_log_f32_e32 v57, v57
	v_exp_f32_e32 v61, v61
	s_nop 0
	v_add_f32_e32 v61, 1.0, v61
	v_rcp_f32_e32 v61, v61
	v_mov_b32_e32 v52, v60
	v_mul_f32_e32 v60, 0x3f317217, v57
	v_mov_b32_e32 v57, v60
	v_fma_f32 v60, v189, v61, v22
	v_mul_f32_e32 v61, v55, v172
	v_mul_f32_e32 v61, 0xbfb8aa3b, v61
	v_exp_f32_e32 v61, v61
	v_log_f32_e32 v60, v60
	v_add_f32_e32 v61, 1.0, v61
	v_rcp_f32_e32 v61, v61
	v_mul_f32_e32 v62, 0x3f317217, v60
	v_fma_f32 v61, v188, v61, v23
	v_mov_b32_e32 v60, v62
	v_mov_b32_e32 v63, v60
	v_mul_f32_e32 v62, v48, v172
	v_mul_f32_e32 v62, 0xbfb8aa3b, v62
	v_exp_f32_e32 v62, v62
	v_log_f32_e32 v61, v61
	v_add_f32_e32 v62, 1.0, v62
	v_rcp_f32_e32 v62, v62
	v_mul_f32_e32 v60, 0x3f317217, v61
	v_fma_f32 v62, v187, v62, v16
	v_mul_f32_e32 v66, v49, v172
	v_mul_f32_e32 v66, 0xbfb8aa3b, v66
	v_log_f32_e32 v62, v62
	v_exp_f32_e32 v66, v66
	v_mov_b32_e32 v61, v60
	v_mul_f32_e32 v60, 0x3f317217, v62
	v_add_f32_e32 v66, 1.0, v66
	v_rcp_f32_e32 v66, v66
	v_cvt_pk_f16_f32 v61, v63, v61
	v_mov_b32_e32 v62, v60
	v_fma_f32 v60, v186, v66, v17
	v_mul_f32_e32 v66, v50, v172
	v_mul_f32_e32 v66, 0xbfb8aa3b, v66
	v_exp_f32_e32 v66, v66
	v_log_f32_e32 v60, v60
	v_add_f32_e32 v66, 1.0, v66
	v_rcp_f32_e32 v66, v66
	v_mul_f32_e32 v67, 0x3f317217, v60
	v_fma_f32 v66, v143, v66, v18
	v_mov_b32_e32 v60, v67
	v_mov_b32_e32 v68, v60
	v_cvt_pk_f16_f32 v62, v62, v68
	v_mul_f32_e32 v67, v51, v172
	v_mul_f32_e32 v67, 0xbfb8aa3b, v67
	v_exp_f32_e32 v67, v67
	v_log_f32_e32 v66, v66
	v_add_f32_e32 v67, 1.0, v67
	v_rcp_f32_e32 v67, v67
	v_mul_f32_e32 v60, 0x3f317217, v66
	v_fma_f32 v67, v142, v67, v19
	v_log_f32_e32 v67, v67
	v_mov_b32_e32 v66, v60
	v_mul_f32_e32 v60, 0x3f317217, v67
	v_mov_b32_e32 v67, v60
	v_cvt_pk_f16_f32 v60, v52, v57
	v_cvt_pk_f16_f32 v63, v66, v67
	global_store_dwordx4 v[64:65], v[60:63], off offset:256 nt

; __device__ __forceinline__ float sigmoidf_(float z) { return __builtin_amdgcn_rcpf(1.0f + __builtin_amdgcn_exp2f(-1.4426950408889634f * z)); }
;     __device__ __forceinline__ float compute(const Pre& p, f32x4 (&acc)[2][2][4][2], const f32x4 (&cv)[2][2], const pg8::Unit& u, int ai, int m, int wr, int wc, int fr, int fq) const {
;     ...
;                     } else if (sec == 1) {
;                         float lf[8];
; #pragma unroll
;                         for (int j = 0; j < 8; ++j) { const float lb = j < 4 ? cv[bj][0][j] : cv[bj][1][j - 4]; const float sg = sigmoidf_(v[j] * rs); lf[j] = __logf(lb + (1.f - lb) * sg); }
;                         u32x4 hw; hw.x = pkh2(lf[0], lf[1]); hw.y = pkh2(lf[2], lf[3]); hw.z = pkh2(lf[4], lf[5]); hw.w = pkh2(lf[6], lf[7]);
;                         __builtin_nontemporal_store(hw, (u32x4*)((_Float16*)out + o));
.LBB0_461:
	v_mul_f32_e32 v51, v45, v170
	v_mul_f32_e32 v51, 0xbfb8aa3b, v51
	v_add_f32_e32 v44, 1.0, v44
	v_exp_f32_e32 v51, v51
	v_rcp_f32_e32 v44, v44
	v_add_f32_e32 v51, 1.0, v51
	v_fma_f32 v44, v201, v44, v36
	v_rcp_f32_e32 v51, v51
	s_nop 0
	v_fma_f32 v51, v199, v51, v37
	v_log_f32_e32 v44, v44
	s_nop 0
	v_mul_f32_e32 v54, 0x3f317217, v44
	v_mul_f32_e32 v55, v46, v170
	v_mul_f32_e32 v55, 0xbfb8aa3b, v55
	v_log_f32_e32 v51, v51
	v_exp_f32_e32 v55, v55
	s_nop 0
	v_add_f32_e32 v55, 1.0, v55
	v_rcp_f32_e32 v55, v55
	v_mov_b32_e32 v44, v54
	v_mul_f32_e32 v54, 0x3f317217, v51
	v_mov_b32_e32 v51, v54
	v_fma_f32 v54, v198, v55, v38
	v_mul_f32_e32 v55, v47, v170
	v_mul_f32_e32 v55, 0xbfb8aa3b, v55
	v_exp_f32_e32 v55, v55
	v_log_f32_e32 v54, v54
	v_add_f32_e32 v55, 1.0, v55
	v_rcp_f32_e32 v55, v55
	v_mul_f32_e32 v56, 0x3f317217, v54
	v_fma_f32 v55, v197, v55, v39
	v_mov_b32_e32 v54, v56
	v_mov_b32_e32 v57, v54
	v_mul_f32_e32 v56, v40, v170
	v_mul_f32_e32 v56, 0xbfb8aa3b, v56
	v_exp_f32_e32 v56, v56
	v_log_f32_e32 v55, v55
	v_add_f32_e32 v56, 1.0, v56
	v_rcp_f32_e32 v56, v56
	v_mul_f32_e32 v54, 0x3f317217, v55
	v_fma_f32 v56, v196, v56, v32
	v_mul_f32_e32 v58, v41, v170
	v_mul_f32_e32 v58, 0xbfb8aa3b, v58
	v_log_f32_e32 v56, v56
	v_exp_f32_e32 v58, v58
	v_mov_b32_e32 v55, v54
	v_mul_f32_e32 v54, 0x3f317217, v56
	v_add_f32_e32 v58, 1.0, v58
	v_rcp_f32_e32 v58, v58
	v_cvt_pk_f16_f32 v55, v57, v55
	v_mov_b32_e32 v56, v54
	v_fma_f32 v54, v195, v58, v33
	v_mul_f32_e32 v58, v42, v170
	v_mul_f32_e32 v58, 0xbfb8aa3b, v58
	v_exp_f32_e32 v58, v58
	v_log_f32_e32 v54, v54
	v_add_f32_e32 v58, 1.0, v58
	v_rcp_f32_e32 v58, v58
	v_mul_f32_e32 v59, 0x3f317217, v54
	v_fma_f32 v58, v194, v58, v34
	v_mov_b32_e32 v54, v59
	v_mov_b32_e32 v60, v54
	v_cvt_pk_f16_f32 v56, v56, v60
	v_mul_f32_e32 v59, v43, v170
	v_mul_f32_e32 v59, 0xbfb8aa3b, v59
	v_exp_f32_e32 v59, v59
	v_log_f32_e32 v58, v58
	v_add_f32_e32 v59, 1.0, v59
	v_rcp_f32_e32 v59, v59
	v_mul_f32_e32 v54, 0x3f317217, v58
	v_fma_f32 v59, v193, v59, v35
	v_log_f32_e32 v59, v59
	v_mov_b32_e32 v58, v54
	v_mul_f32_e32 v54, 0x3f317217, v59
	v_mov_b32_e32 v59, v54
	v_cvt_pk_f16_f32 v54, v44, v51
	v_cvt_pk_f16_f32 v57, v58, v59
	v_lshl_add_u64 v[58:59], v[52:53], 1, s[70:71]
	global_store_dwordx4 v[58:59], v[54:57], off nt

; __device__ __forceinline__ float sigmoidf_(float z) { return __builtin_amdgcn_rcpf(1.0f + __builtin_amdgcn_exp2f(-1.4426950408889634f * z)); }
;     __device__ __forceinline__ float compute(const Pre& p, f32x4 (&acc)[2][2][4][2], const f32x4 (&cv)[2][2], const pg8::Unit& u, int ai, int m, int wr, int wc, int fr, int fq) const {
;     ...
;                     } else if (sec == 1) {
;                         float lf[8];
; #pragma unroll
;                         for (int j = 0; j < 8; ++j) { const float lb = j < 4 ? cv[bj][0][j] : cv[bj][1][j - 4]; const float sg = sigmoidf_(v[j] * rs); lf[j] = __logf(lb + (1.f - lb) * sg); }
;                         u32x4 hw; hw.x = pkh2(lf[0], lf[1]); hw.y = pkh2(lf[2], lf[3]); hw.z = pkh2(lf[4], lf[5]); hw.w = pkh2(lf[6], lf[7]);
;                         __builtin_nontemporal_store(hw, (u32x4*)((_Float16*)out + o));
.LBB0_477:
	v_mul_f32_e32 v41, v29, v170
	v_mul_f32_e32 v41, 0xbfb8aa3b, v41
	v_add_f32_e32 v28, 1.0, v28
	v_exp_f32_e32 v41, v41
	v_rcp_f32_e32 v28, v28
	v_lshl_add_u64 v[48:49], v[48:49], 0, v[168:169]
	v_lshl_add_u64 v[48:49], v[48:49], 1, s[70:71]
	v_add_f32_e32 v41, 1.0, v41
	v_fma_f32 v28, v202, v28, v20
	v_rcp_f32_e32 v41, v41
	s_nop 0
	v_fma_f32 v41, v200, v41, v21
	v_log_f32_e32 v28, v28
	s_nop 0
	v_mul_f32_e32 v44, 0x3f317217, v28
	v_mul_f32_e32 v45, v30, v170
	v_mul_f32_e32 v45, 0xbfb8aa3b, v45
	v_log_f32_e32 v41, v41
	v_exp_f32_e32 v45, v45
	s_nop 0
	v_add_f32_e32 v45, 1.0, v45
	v_rcp_f32_e32 v45, v45
	v_mov_b32_e32 v28, v44
	v_mul_f32_e32 v44, 0x3f317217, v41
	v_mov_b32_e32 v41, v44
	v_fma_f32 v44, v189, v45, v22
	v_mul_f32_e32 v45, v31, v170
	v_mul_f32_e32 v45, 0xbfb8aa3b, v45
	v_exp_f32_e32 v45, v45
	v_log_f32_e32 v44, v44
	v_add_f32_e32 v45, 1.0, v45
	v_rcp_f32_e32 v45, v45
	v_mul_f32_e32 v46, 0x3f317217, v44
	v_fma_f32 v45, v188, v45, v23
	v_mov_b32_e32 v44, v46
	v_mov_b32_e32 v47, v44
	v_mul_f32_e32 v46, v24, v170
	v_mul_f32_e32 v46, 0xbfb8aa3b, v46
	v_exp_f32_e32 v46, v46
	v_log_f32_e32 v45, v45
	v_add_f32_e32 v46, 1.0, v46
	v_rcp_f32_e32 v46, v46
	v_mul_f32_e32 v44, 0x3f317217, v45
	v_fma_f32 v46, v187, v46, v16
	v_mul_f32_e32 v50, v25, v170
	v_mul_f32_e32 v50, 0xbfb8aa3b, v50
	v_log_f32_e32 v46, v46
	v_exp_f32_e32 v50, v50
	v_mov_b32_e32 v45, v44
	v_mul_f32_e32 v44, 0x3f317217, v46
	v_add_f32_e32 v50, 1.0, v50
	v_rcp_f32_e32 v50, v50
	v_cvt_pk_f16_f32 v45, v47, v45
	v_mov_b32_e32 v46, v44
	v_fma_f32 v44, v186, v50, v17
	v_mul_f32_e32 v50, v26, v170
	v_mul_f32_e32 v50, 0xbfb8aa3b, v50
	v_exp_f32_e32 v50, v50
	v_log_f32_e32 v44, v44
	v_add_f32_e32 v50, 1.0, v50
	v_rcp_f32_e32 v50, v50
	v_mul_f32_e32 v51, 0x3f317217, v44
	v_fma_f32 v50, v143, v50, v18
	v_mov_b32_e32 v44, v51
	v_mov_b32_e32 v52, v44
	v_cvt_pk_f16_f32 v46, v46, v52
	v_mul_f32_e32 v51, v27, v170
	v_mul_f32_e32 v51, 0xbfb8aa3b, v51
	v_exp_f32_e32 v51, v51
	v_log_f32_e32 v50, v50
	v_add_f32_e32 v51, 1.0, v51
	v_rcp_f32_e32 v51, v51
	v_mul_f32_e32 v44, 0x3f317217, v50
	v_fma_f32 v51, v142, v51, v19
	v_log_f32_e32 v51, v51
	v_mov_b32_e32 v50, v44
	v_mul_f32_e32 v44, 0x3f317217, v51
	v_mov_b32_e32 v51, v44
	v_cvt_pk_f16_f32 v44, v28, v41
	v_cvt_pk_f16_f32 v47, v50, v51
	global_store_dwordx4 v[48:49], v[44:47], off offset:256 nt

; __device__ __forceinline__ float sigmoidf_(float z) { return __builtin_amdgcn_rcpf(1.0f + __builtin_amdgcn_exp2f(-1.4426950408889634f * z)); }
;     __device__ __forceinline__ float compute(const Pre& p, f32x4 (&acc)[2][2][4][2], const f32x4 (&cv)[2][2], const pg8::Unit& u, int ai, int m, int wr, int wc, int fr, int fq) const {
;     ...
;                     } else if (sec == 1) {
;                         float lf[8];
; #pragma unroll
;                         for (int j = 0; j < 8; ++j) { const float lb = j < 4 ? cv[bj][0][j] : cv[bj][1][j - 4]; const float sg = sigmoidf_(v[j] * rs); lf[j] = __logf(lb + (1.f - lb) * sg); }
;                         u32x4 hw; hw.x = pkh2(lf[0], lf[1]); hw.y = pkh2(lf[2], lf[3]); hw.z = pkh2(lf[4], lf[5]); hw.w = pkh2(lf[6], lf[7]);
;                         __builtin_nontemporal_store(hw, (u32x4*)((_Float16*)out + o));
.LBB0_493:
	v_mul_f32_e32 v27, v13, v166
	v_add_f32_e32 v12, 1.0, v12
	v_mul_f32_e32 v27, 0xbfb8aa3b, v27
	v_rcp_f32_e32 v12, v12
	v_exp_f32_e32 v27, v27
	v_mul_f32_e32 v31, v14, v166
	v_mul_f32_e32 v31, 0xbfb8aa3b, v31
	v_fmac_f32_e32 v36, v201, v12
	v_add_f32_e32 v27, 1.0, v27
	v_rcp_f32_e32 v27, v27
	v_exp_f32_e32 v31, v31
	v_mov_b32_e32 v12, v36
	v_log_f32_e32 v12, v12
	v_fmac_f32_e32 v37, v199, v27
	v_add_f32_e32 v31, 1.0, v31
	v_mul_f32_e32 v30, 0x3f317217, v12
	v_mov_b32_e32 v27, v37
	v_log_f32_e32 v27, v27
	v_rcp_f32_e32 v31, v31
	v_mov_b32_e32 v12, v30
	v_mul_f32_e32 v30, 0x3f317217, v27
	v_fmac_f32_e32 v38, v198, v31
	v_mul_f32_e32 v31, v15, v166
	v_mov_b32_e32 v27, v30
	v_mul_f32_e32 v31, 0xbfb8aa3b, v31
	v_mov_b32_e32 v30, v38
	v_log_f32_e32 v30, v30
	v_exp_f32_e32 v31, v31
	v_mul_f32_e32 v36, 0x3f317217, v30
	v_add_f32_e32 v31, 1.0, v31
	v_rcp_f32_e32 v31, v31
	v_mov_b32_e32 v30, v36
	v_mul_f32_e32 v36, v8, v166
	v_mul_f32_e32 v36, 0xbfb8aa3b, v36
	v_exp_f32_e32 v36, v36
	v_fmac_f32_e32 v39, v197, v31
	v_mov_b32_e32 v37, v30
	v_add_f32_e32 v36, 1.0, v36
	v_rcp_f32_e32 v36, v36
	v_mov_b32_e32 v31, v39
	v_log_f32_e32 v31, v31
	v_fmac_f32_e32 v32, v196, v36
	v_mul_f32_e32 v30, 0x3f317217, v31
	v_mul_f32_e32 v36, v9, v166
	v_mul_f32_e32 v36, 0xbfb8aa3b, v36
	v_exp_f32_e32 v36, v36
	v_log_f32_e32 v32, v32
	v_add_f32_e32 v36, 1.0, v36
	v_rcp_f32_e32 v36, v36
	v_mov_b32_e32 v31, v30
	v_mul_f32_e32 v30, 0x3f317217, v32
	v_fmac_f32_e32 v33, v195, v36
	v_cvt_pk_f16_f32 v31, v37, v31
	v_mov_b32_e32 v32, v30
	v_mov_b32_e32 v30, v33
	v_mul_f32_e32 v33, v10, v166
	v_mul_f32_e32 v33, 0xbfb8aa3b, v33
	v_exp_f32_e32 v33, v33
	v_log_f32_e32 v30, v30
	v_add_f32_e32 v33, 1.0, v33
	v_rcp_f32_e32 v33, v33
	v_mul_f32_e32 v36, 0x3f317217, v30
	v_fmac_f32_e32 v34, v194, v33
	v_mov_b32_e32 v30, v36
	v_mov_b32_e32 v36, v30
	v_mov_b32_e32 v33, v34
	v_mul_f32_e32 v34, v11, v166
	v_mul_f32_e32 v34, 0xbfb8aa3b, v34
	v_exp_f32_e32 v34, v34
	v_log_f32_e32 v33, v33
	v_cvt_pk_f16_f32 v32, v32, v36
	v_add_f32_e32 v34, 1.0, v34
	v_rcp_f32_e32 v34, v34
	v_mul_f32_e32 v30, 0x3f317217, v33
	v_fmac_f32_e32 v35, v193, v34
	v_mov_b32_e32 v34, v35
	v_log_f32_e32 v34, v34
	v_mov_b32_e32 v33, v30
	v_mul_f32_e32 v30, 0x3f317217, v34
	v_mov_b32_e32 v34, v30
	v_cvt_pk_f16_f32 v30, v12, v27
	v_cvt_pk_f16_f32 v33, v33, v34
	v_lshl_add_u64 v[34:35], v[28:29], 1, s[70:71]
	global_store_dwordx4 v[34:35], v[30:33], off nt

; __device__ __forceinline__ float sigmoidf_(float z) { return __builtin_amdgcn_rcpf(1.0f + __builtin_amdgcn_exp2f(-1.4426950408889634f * z)); }
;     __device__ __forceinline__ float compute(const Pre& p, f32x4 (&acc)[2][2][4][2], const f32x4 (&cv)[2][2], const pg8::Unit& u, int ai, int m, int wr, int wc, int fr, int fq) const {
;     ...
;                     } else if (sec == 1) {
;                         float lf[8];
; #pragma unroll
;                         for (int j = 0; j < 8; ++j) { const float lb = j < 4 ? cv[bj][0][j] : cv[bj][1][j - 4]; const float sg = sigmoidf_(v[j] * rs); lf[j] = __logf(lb + (1.f - lb) * sg); }
;                         u32x4 hw; hw.x = pkh2(lf[0], lf[1]); hw.y = pkh2(lf[2], lf[3]); hw.z = pkh2(lf[4], lf[5]); hw.w = pkh2(lf[6], lf[7]);
;                         __builtin_nontemporal_store(hw, (u32x4*)((_Float16*)out + o));
.LBB0_509:
	v_mul_f32_e32 v9, v5, v166
	v_add_f32_e32 v4, 1.0, v4
	v_mul_f32_e32 v9, 0xbfb8aa3b, v9
	v_rcp_f32_e32 v4, v4
	v_exp_f32_e32 v9, v9
	v_mul_f32_e32 v13, v6, v166
	v_mul_f32_e32 v13, 0xbfb8aa3b, v13
	v_fmac_f32_e32 v20, v202, v4
	v_add_f32_e32 v9, 1.0, v9
	v_rcp_f32_e32 v9, v9
	v_exp_f32_e32 v13, v13
	v_mov_b32_e32 v4, v20
	v_log_f32_e32 v4, v4
	v_fmac_f32_e32 v21, v200, v9
	v_add_f32_e32 v13, 1.0, v13
	v_mul_f32_e32 v12, 0x3f317217, v4
	v_mov_b32_e32 v9, v21
	v_log_f32_e32 v9, v9
	v_rcp_f32_e32 v13, v13
	v_mov_b32_e32 v4, v12
	v_mul_f32_e32 v12, 0x3f317217, v9
	v_fmac_f32_e32 v22, v189, v13
	v_mul_f32_e32 v13, v7, v166
	v_mov_b32_e32 v9, v12
	v_mul_f32_e32 v13, 0xbfb8aa3b, v13
	v_mov_b32_e32 v12, v22
	v_log_f32_e32 v12, v12
	v_exp_f32_e32 v13, v13
	v_mul_f32_e32 v14, 0x3f317217, v12
	v_add_f32_e32 v13, 1.0, v13
	v_rcp_f32_e32 v13, v13
	v_mov_b32_e32 v12, v14
	v_mul_f32_e32 v14, v0, v166
	v_mul_f32_e32 v14, 0xbfb8aa3b, v14
	v_exp_f32_e32 v14, v14
	v_fmac_f32_e32 v23, v188, v13
	v_mov_b32_e32 v15, v12
	v_add_f32_e32 v14, 1.0, v14
	v_rcp_f32_e32 v14, v14
	v_mov_b32_e32 v13, v23
	v_log_f32_e32 v13, v13
	v_fmac_f32_e32 v16, v187, v14
	v_mul_f32_e32 v12, 0x3f317217, v13
	v_mov_b32_e32 v14, v16
	v_mul_f32_e32 v16, v1, v166
	v_mul_f32_e32 v16, 0xbfb8aa3b, v16
	v_exp_f32_e32 v16, v16
	v_log_f32_e32 v14, v14
	v_add_f32_e32 v16, 1.0, v16
	v_rcp_f32_e32 v16, v16
	v_mov_b32_e32 v13, v12
	v_mul_f32_e32 v12, 0x3f317217, v14
	v_fmac_f32_e32 v17, v186, v16
	v_mul_f32_e32 v16, v2, v166
	v_mov_b32_e32 v14, v12
	v_mul_f32_e32 v16, 0xbfb8aa3b, v16
	v_mov_b32_e32 v12, v17
	v_log_f32_e32 v12, v12
	v_exp_f32_e32 v16, v16
	v_cvt_pk_f16_f32 v13, v15, v13
	v_mul_f32_e32 v17, 0x3f317217, v12
	v_add_f32_e32 v16, 1.0, v16
	v_rcp_f32_e32 v16, v16
	v_mov_b32_e32 v12, v17
	v_mul_f32_e32 v17, v3, v166
	v_mul_f32_e32 v17, 0xbfb8aa3b, v17
	v_exp_f32_e32 v17, v17
	v_fmac_f32_e32 v18, v143, v16
	v_add_f32_e32 v17, 1.0, v17
	v_rcp_f32_e32 v17, v17
	v_mov_b32_e32 v16, v18
	v_log_f32_e32 v16, v16
	v_fmac_f32_e32 v19, v142, v17
	v_mov_b32_e32 v18, v12
	v_mul_f32_e32 v12, 0x3f317217, v16
	v_mov_b32_e32 v17, v19
	v_log_f32_e32 v17, v17
	v_cvt_pk_f16_f32 v14, v14, v18
	v_mov_b32_e32 v16, v12
	v_mul_f32_e32 v12, 0x3f317217, v17
	v_mov_b32_e32 v17, v12
	v_cvt_pk_f16_f32 v15, v16, v17
	v_lshl_add_u64 v[16:17], v[24:25], 0, v[168:169]
	v_cvt_pk_f16_f32 v12, v4, v9
	v_lshl_add_u64 v[16:17], v[16:17], 1, s[70:71]
	global_store_dwordx4 v[16:17], v[12:15], off offset:256 nt
